# attention steady loop: m0 save/restore around the four LDS-DMA issues dropped (m0 is only used as the DMA LDS base)
# baseline (speedup 1.0000x reference)
.LBB0_381:
	v_add_u32_e32 v183, s20, v209
	ds_read_b64_tr_b16 v[178:179], v183 offset:24576
	ds_read_b64_tr_b16 v[180:181], v183 offset:25088
	s_waitcnt lgkmcnt(9)
	v_mfma_f32_32x32x16_bf16 v[98:113], v[174:177], v[142:145], v[34:49]
	v_add_f32_e32 v82, v66, v67
	v_add_f32_e32 v82, v68, v82
	v_add_f32_e32 v82, v69, v82
	v_add_f32_e32 v82, v70, v82
	v_add_f32_e32 v82, v71, v82
	v_cvt_pk_bf16_f32 v138, v66, v67
	v_cvt_pk_bf16_f32 v139, v68, v69
	ds_read_b64_tr_b16 v[174:175], v183 offset:28672
	ds_read_b64_tr_b16 v[176:177], v183 offset:29184
	v_add_f32_e32 v66, v72, v82
	s_waitcnt lgkmcnt(10)
	v_mfma_f32_32x32x16_bf16 v[82:97], v[170:173], v[142:145], v[34:49]
	v_add_f32_e32 v66, v73, v66
	v_add_f32_e32 v66, v74, v66
	v_add_f32_e32 v114, v75, v66
	v_cvt_pk_bf16_f32 v140, v70, v71
	v_cvt_pk_bf16_f32 v141, v72, v73
	ds_read_b64_tr_b16 v[66:67], v183 offset:25600
	ds_read_b64_tr_b16 v[68:69], v183 offset:26112
	s_waitcnt lgkmcnt(11)
	v_mfma_f32_32x32x16_bf16 v[98:113], v[166:169], v[134:137], v[98:113]
	v_add_f32_e32 v70, v76, v114
	v_add_f32_e32 v70, v77, v70
	v_add_f32_e32 v70, v78, v70
	v_add_f32_e32 v114, v79, v70
	v_cvt_pk_bf16_f32 v130, v74, v75
	v_cvt_pk_bf16_f32 v131, v76, v77
	ds_read_b64_tr_b16 v[70:71], v183 offset:29696
	ds_read_b64_tr_b16 v[72:73], v183 offset:30208
	s_waitcnt lgkmcnt(12)
	v_mfma_f32_32x32x16_bf16 v[82:97], v[162:165], v[134:137], v[82:97]
	v_add_f32_e32 v74, v80, v114
	v_add_f32_e32 v74, v81, v74
	v_add_f32_e32 v74, v50, v74
	v_add_f32_e32 v114, v51, v74
	v_cvt_pk_bf16_f32 v132, v78, v79
	v_cvt_pk_bf16_f32 v133, v80, v81
	ds_read_b64_tr_b16 v[74:75], v183 offset:26624
	ds_read_b64_tr_b16 v[76:77], v183 offset:27136
	s_waitcnt lgkmcnt(13)
	v_mfma_f32_32x32x16_bf16 v[98:113], v[158:161], v[126:129], v[98:113]
	v_add_f32_e32 v78, v52, v114
	v_add_f32_e32 v78, v53, v78
	v_add_f32_e32 v78, v54, v78
	v_add_f32_e32 v78, v55, v78
	v_cvt_pk_bf16_f32 v122, v50, v51
	v_cvt_pk_bf16_f32 v123, v52, v53
	ds_read_b64_tr_b16 v[50:51], v183 offset:30720
	ds_read_b64_tr_b16 v[52:53], v183 offset:31232
	s_waitcnt lgkmcnt(14)
	v_mfma_f32_32x32x16_bf16 v[82:97], v[154:157], v[126:129], v[82:97]
	v_add_f32_e32 v78, v56, v78
	v_add_f32_e32 v78, v57, v78
	v_add_f32_e32 v78, v58, v78
	v_add_f32_e32 v78, v59, v78
	v_cvt_pk_bf16_f32 v124, v54, v55
	v_cvt_pk_bf16_f32 v125, v56, v57
	ds_read_b64_tr_b16 v[54:55], v183 offset:27648
	ds_read_b64_tr_b16 v[56:57], v183 offset:28160
	s_waitcnt lgkmcnt(14)
	v_mfma_f32_32x32x16_bf16 v[98:113], v[150:153], v[118:121], v[98:113]
	v_add_f32_e32 v78, v60, v78
	v_add_f32_e32 v78, v61, v78
	v_add_f32_e32 v78, v62, v78
	v_add_f32_e32 v78, v63, v78
	v_cvt_pk_bf16_f32 v114, v58, v59
	v_cvt_pk_bf16_f32 v115, v60, v61
	ds_read_b64_tr_b16 v[58:59], v183 offset:31744
	ds_read_b64_tr_b16 v[60:61], v183 offset:32256
	v_mfma_f32_32x32x16_bf16 v[82:97], v[146:149], v[118:121], v[82:97]
	v_add_f32_e32 v78, v64, v78
	v_add_f32_e32 v78, v65, v78
	v_cvt_pk_bf16_f32 v116, v62, v63
	v_cvt_pk_bf16_f32 v117, v64, v65
	s_add_i32 s20, s72, s29
	s_mov_b32 m0, s20
	s_nop 0
	global_load_lds_dwordx4 v226, s[98:99]
	s_add_i32 s20, s36, s30
	s_mov_b32 m0, s20
	s_nop 0
	global_load_lds_dwordx4 v228, s[100:101]
	v_max_f32_e32 v62, v98, v99
	v_max3_f32 v63, v100, v101, v83
	v_max3_f32 v62, v62, v82, v84
	v_max3_f32 v62, v62, v85, v102
	v_max3_f32 v63, v63, v104, v105
	v_max3_f32 v62, v62, v103, v86
	v_max3_f32 v63, v63, v88, v89
	v_max3_f32 v62, v62, v87, v106
	v_max3_f32 v63, v63, v108, v109
	v_max3_f32 v62, v62, v107, v90
	v_max3_f32 v63, v63, v92, v93
	v_max3_f32 v62, v62, v91, v110
	v_max3_f32 v63, v63, v112, v113
	v_max3_f32 v62, v62, v111, v94
	v_max3_f32 v63, v63, v96, v97
	v_max3_f32 v62, v62, v95, v63
	v_cmp_lt_f32_e32 vcc, s69, v62
	s_cmp_lg_u64 vcc, 0
	v_add_f32_e32 v183, v194, v78
	s_cselect_b64 s[20:21], -1, 0
	s_cbranch_vccnz .LBB0_389

.LBB0_384:
	s_add_i32 s20, s36, 0x2000
	s_cmpk_lg_i32 s36, 0x4000
	s_cselect_b32 s35, s20, 0
	v_add_u32_e32 v194, s72, v209
	ds_read_b64_tr_b16 v[150:151], v194 offset:24576
	ds_read_b64_tr_b16 v[152:153], v194 offset:25088
	s_waitcnt lgkmcnt(9)
	v_mfma_f32_32x32x16_bf16 v[66:81], v[62:65], v[142:145], v[34:49]
	v_add_f32_e32 v50, v98, v99
	v_add_f32_e32 v50, v100, v50
	v_add_f32_e32 v50, v101, v50
	v_add_f32_e32 v50, v102, v50
	v_add_f32_e32 v50, v103, v50
	v_cvt_pk_bf16_f32 v138, v98, v99
	v_cvt_pk_bf16_f32 v139, v100, v101
	ds_read_b64_tr_b16 v[146:147], v194 offset:28672
	ds_read_b64_tr_b16 v[148:149], v194 offset:29184
	v_add_f32_e32 v50, v104, v50
	v_add_f32_e32 v50, v105, v50
	v_add_f32_e32 v50, v106, v50
	v_add_f32_e32 v114, v107, v50
	s_waitcnt lgkmcnt(10)
	v_mfma_f32_32x32x16_bf16 v[50:65], v[174:177], v[142:145], v[34:49]
	v_cvt_pk_bf16_f32 v140, v102, v103
	v_cvt_pk_bf16_f32 v141, v104, v105
	ds_read_b64_tr_b16 v[98:99], v194 offset:25600
	ds_read_b64_tr_b16 v[100:101], v194 offset:26112
	s_waitcnt lgkmcnt(11)
	v_mfma_f32_32x32x16_bf16 v[66:81], v[178:181], v[134:137], v[66:81]
	v_add_f32_e32 v102, v108, v114
	v_add_f32_e32 v102, v109, v102
	v_add_f32_e32 v102, v110, v102
	v_add_f32_e32 v114, v111, v102
	v_cvt_pk_bf16_f32 v130, v106, v107
	v_cvt_pk_bf16_f32 v131, v108, v109
	ds_read_b64_tr_b16 v[102:103], v194 offset:29696
	ds_read_b64_tr_b16 v[104:105], v194 offset:30208
	s_waitcnt lgkmcnt(12)
	v_mfma_f32_32x32x16_bf16 v[50:65], v[170:173], v[134:137], v[50:65]
	v_add_f32_e32 v106, v112, v114
	v_add_f32_e32 v106, v113, v106
	v_add_f32_e32 v106, v82, v106
	v_add_f32_e32 v114, v83, v106
	v_cvt_pk_bf16_f32 v132, v110, v111
	v_cvt_pk_bf16_f32 v133, v112, v113
	ds_read_b64_tr_b16 v[106:107], v194 offset:26624
	ds_read_b64_tr_b16 v[108:109], v194 offset:27136
	s_waitcnt lgkmcnt(13)
	v_mfma_f32_32x32x16_bf16 v[66:81], v[166:169], v[126:129], v[66:81]
	v_add_f32_e32 v110, v84, v114
	v_add_f32_e32 v110, v85, v110
	v_add_f32_e32 v110, v86, v110
	v_add_f32_e32 v110, v87, v110
	v_cvt_pk_bf16_f32 v122, v82, v83
	v_cvt_pk_bf16_f32 v123, v84, v85
	ds_read_b64_tr_b16 v[82:83], v194 offset:30720
	ds_read_b64_tr_b16 v[84:85], v194 offset:31232
	s_waitcnt lgkmcnt(14)
	v_mfma_f32_32x32x16_bf16 v[50:65], v[162:165], v[126:129], v[50:65]
	v_add_f32_e32 v110, v88, v110
	v_add_f32_e32 v110, v89, v110
	v_add_f32_e32 v110, v90, v110
	v_add_f32_e32 v110, v91, v110
	v_cvt_pk_bf16_f32 v124, v86, v87
	v_cvt_pk_bf16_f32 v125, v88, v89
	ds_read_b64_tr_b16 v[86:87], v194 offset:27648
	ds_read_b64_tr_b16 v[88:89], v194 offset:28160
	s_waitcnt lgkmcnt(14)
	v_mfma_f32_32x32x16_bf16 v[66:81], v[158:161], v[118:121], v[66:81]
	v_add_f32_e32 v110, v92, v110
	v_add_f32_e32 v110, v93, v110
	v_add_f32_e32 v110, v94, v110
	v_add_f32_e32 v110, v95, v110
	v_cvt_pk_bf16_f32 v114, v90, v91
	v_cvt_pk_bf16_f32 v115, v92, v93
	ds_read_b64_tr_b16 v[90:91], v194 offset:31744
	ds_read_b64_tr_b16 v[92:93], v194 offset:32256
	v_mfma_f32_32x32x16_bf16 v[50:65], v[154:157], v[118:121], v[50:65]
	v_add_f32_e32 v110, v96, v110
	v_add_f32_e32 v110, v97, v110
	v_cvt_pk_bf16_f32 v116, v94, v95
	v_cvt_pk_bf16_f32 v117, v96, v97
	s_add_i32 s20, s36, s29
	s_mov_b32 m0, s20
	s_nop 0
	global_load_lds_dwordx4 v227, s[98:99]
	s_add_i32 s20, s35, s30
	s_mov_b32 m0, s20
	s_nop 0
	global_load_lds_dwordx4 v229, s[100:101]
	v_max_f32_e32 v94, v66, v67
	v_max3_f32 v95, v68, v69, v51
	v_max3_f32 v94, v94, v50, v52
	v_max3_f32 v94, v94, v53, v70
	v_max3_f32 v95, v95, v72, v73
	v_max3_f32 v94, v94, v71, v54
	v_max3_f32 v95, v95, v56, v57
	v_max3_f32 v94, v94, v55, v74
	v_max3_f32 v95, v95, v76, v77
	v_max3_f32 v94, v94, v75, v58
	v_max3_f32 v95, v95, v60, v61
	v_max3_f32 v94, v94, v59, v78
	v_max3_f32 v95, v95, v80, v81
	v_max3_f32 v94, v94, v79, v62
	v_max3_f32 v95, v95, v64, v65
	v_max3_f32 v94, v94, v63, v95
	v_cmp_lt_f32_e32 vcc, s69, v94
	s_cmp_lg_u64 vcc, 0
	v_add_f32_e32 v194, v183, v110
	s_cselect_b64 s[20:21], -1, 0
	s_cbranch_vccnz .LBB0_392
